# attention loop: loop-edge block (exit test, slot rotation, next-tile LDS bases, active test) issued before the last P.V MFMA (on v44)
# speedup vs baseline: 1.0002x; 1.0002x over previous
; template <int DQK, bool MLA> ...
;     ...
;     auto substep = [&](f32x16& a, f32x16& b, int knext_ofs, int vofs, int h, int kafter_ofs) __attribute__((always_inline)) {
;         const LAS unsigned char* kb = lds + knext_ofs + r32 * KPITCH + hi * 16;
;         const LAS unsigned char* vb = lds + vofs + r32 * 144 + hi * 16 + h * 64;
;         u32x4 pw0, pw1; bf16x8 vf0[4], vf1[4], kr[3];
;         kr[0] = kp0; kr[1] = kp1;
;         float rs0 = rs_early;
;         __builtin_amdgcn_sched_barrier(0);
; #pragma unroll
;         for (int d0 = 0; d0 < KS; ++d0) {
;             if (d0 + 2 < KS) kr[(d0 + 2) % 3] = *(const LAS bf16x8*)(kb + (d0 + 2) * 32);
;             if (d0 == KS - 3) {
; #pragma unroll
;                 for (int d = 0; d < 4; ++d) vf0[d] = *(const LAS bf16x8*)(vb + d * 4608);
;             }
;             if (d0 == 0) { const f32x16 z16 = {0.f, 0.f, 0.f, 0.f, 0.f, 0.f, 0.f, 0.f, 0.f, 0.f, 0.f, 0.f, 0.f, 0.f, 0.f, 0.f};
;                 b = __builtin_amdgcn_mfma_f32_32x32x16_bf16(kr[0], qf[0], z16, 0, 0, 0); }
;             else b = __builtin_amdgcn_mfma_f32_32x32x16_bf16(kr[d0 % 3], qf[d0], b, 0, 0, 0);
; #pragma unroll
;             for (int e = 6 + (10 * d0) / KS; e < 6 + (10 * (d0 + 1)) / KS; ++e) {
;                 const float x = __builtin_amdgcn_exp2f(a[e]);
;                 a[e] = x;
;                 rs0 += x;
;                 if (e == 7)  { pw0.x = pk(a[0], a[1]); pw0.y = pk(a[2], a[3]);   pw0.z = pk(a[4], a[5]);   pw0.w = pk(a[6], a[7]); }
;                 if (e == 15) { pw1.x = pk(a[8], a[9]); pw1.y = pk(a[10], a[11]); pw1.z = pk(a[12], a[13]); pw1.w = pk(a[14], a[15]); }
;             }
;             __builtin_amdgcn_sched_barrier(0);
;         }
;         l_run += rs0;
;         float rs_n = 0.f;
; #pragma unroll
;         for (int kk = 0; kk < 2; ++kk) {
;             if (kk == 0) {
; #pragma unroll
;                 for (int d = 0; d < 4; ++d) vf1[d] = *(const LAS bf16x8*)(vb + d * 4608 + 32);
;             } else { const LAS unsigned char* ka = lds + kafter_ofs + r32 * KPITCH + hi * 16; kp0 = *(const LAS bf16x8*)(ka); kp1 = *(const LAS bf16x8*)(ka + 32); }
;             const bf16x8 pb = __builtin_bit_cast(bf16x8, kk ? pw1 : pw0);
; #pragma unroll
;             for (int d = 0; d < 4; ++d) {
;                 o[d] = __builtin_amdgcn_mfma_f32_32x32x16_bf16(kk ? vf1[d] : vf0[d], pb, o[d], 0, 0, 0);
.Lattn_ld6_skip:
	s_or_b64 exec, exec, s[34:35]
	ds_read_b128 v[160:163], v193 offset:13024
	v_exp_f32_e32 v195, v74
	s_nop 0
	v_add_f32_e32 v72, v195, v72
	v_lshl_add_u64 v[190:191], v[190:191], 0, s[20:21]
	s_waitcnt lgkmcnt(1)
	v_mfma_f32_32x32x16_bf16 v[80:95], v[210:213], v[124:127], v[80:95]
	ds_read_b128 v[68:71], v193 offset:13056
	s_waitcnt lgkmcnt(1)
	v_mfma_f32_32x32x16_bf16 v[80:95], v[160:163], v[128:131], v[80:95]
	v_exp_f32_e32 v196, v75
	ds_read_b128 v[210:213], v193 offset:13088
	v_add_f32_e32 v160, v196, v72
	s_waitcnt lgkmcnt(1)
	v_mfma_f32_32x32x16_bf16 v[80:95], v[68:71], v[136:139], v[80:95]
	ds_read_b128 v[72:75], v193 offset:13120
	v_exp_f32_e32 v76, v76
	s_nop 0
	v_add_f32_e32 v197, v76, v160
	ds_read_b128 v[68:71], v193 offset:13152
	ds_read_b128 v[160:163], v208
	ds_read_b128 v[214:217], v208 offset:4608
	ds_read_b128 v[218:221], v208 offset:9216
	ds_read_b128 v[222:225], v208 offset:13824
	s_waitcnt lgkmcnt(6)
	v_mfma_f32_32x32x16_bf16 v[80:95], v[210:213], v[144:147], v[80:95]
	v_exp_f32_e32 v77, v77
	s_nop 0
	v_add_f32_e32 v193, v77, v197
	s_waitcnt lgkmcnt(5)
	v_mfma_f32_32x32x16_bf16 v[80:95], v[72:75], v[132:135], v[80:95]
	v_exp_f32_e32 v72, v78
	s_nop 0
	v_add_f32_e32 v73, v72, v193
	s_waitcnt lgkmcnt(4)
	v_mfma_f32_32x32x16_bf16 v[80:95], v[68:71], v[140:143], v[80:95]
	v_exp_f32_e32 v71, v79
	v_cvt_pk_bf16_f32 v68, v194, v186
	v_cvt_pk_bf16_f32 v69, v195, v196
	v_cvt_pk_bf16_f32 v70, v76, v77
	v_add_f32_e32 v73, v71, v73
	v_cvt_pk_bf16_f32 v71, v72, v71
	s_waitcnt lgkmcnt(3)
	v_mfma_f32_32x32x16_bf16 v[48:63], v[160:163], v[64:67], v[48:63]
	v_add_f32_e32 v187, v187, v73
	ds_read_b128 v[72:75], v208 offset:32
	ds_read_b128 v[76:79], v208 offset:4640
	ds_read_b128 v[160:163], v208 offset:9248
	ds_read_b128 v[210:213], v208 offset:13856
	s_nop 1
	v_exp_f32_e32 v186, v80
	v_exp_f32_e32 v193, v81
	s_waitcnt lgkmcnt(6)
	v_mfma_f32_32x32x16_bf16 v[32:47], v[214:217], v[64:67], v[32:47]
	s_waitcnt lgkmcnt(5)
	v_mfma_f32_32x32x16_bf16 v[16:31], v[218:221], v[64:67], v[16:31]
	s_waitcnt lgkmcnt(4)
	v_mfma_f32_32x32x16_bf16 v[0:15], v[222:225], v[64:67], v[0:15]
	s_waitcnt lgkmcnt(3)
	v_mfma_f32_32x32x16_bf16 v[48:63], v[72:75], v[68:71], v[48:63]
	v_exp_f32_e32 v195, v82
	v_add_u32_e32 v194, s72, v183
	v_exp_f32_e32 v196, v83
	ds_read_b128 v[64:67], v194
	ds_read_b128 v[214:217], v194 offset:32
	v_exp_f32_e32 v84, v84
	v_add_f32_e32 v72, 0, v186
	v_exp_f32_e32 v85, v85
	s_waitcnt lgkmcnt(4)
	v_mfma_f32_32x32x16_bf16 v[32:47], v[76:79], v[68:71], v[32:47]
	v_add_f32_e32 v72, v193, v72
	v_add_f32_e32 v72, v195, v72
	v_add_f32_e32 v72, v196, v72
	v_add_f32_e32 v72, v84, v72
	v_add_f32_e32 v197, v85, v72
	s_waitcnt lgkmcnt(3)
	v_mfma_f32_32x32x16_bf16 v[16:31], v[160:163], v[68:71], v[16:31]
	s_waitcnt lgkmcnt(2)
	v_mfma_f32_32x32x16_bf16 v[0:15], v[210:213], v[68:71], v[0:15]
	s_waitcnt lgkmcnt(1)
	v_mfma_f32_32x32x16_bf16 v[64:79], v[64:67], v[100:103], 0
	ds_read_b128 v[80:83], v194 offset:64
	s_waitcnt lgkmcnt(1)
	v_mfma_f32_32x32x16_bf16 v[64:79], v[214:217], v[104:107], v[64:79]
	ds_read_b128 v[160:163], v194 offset:96
	v_exp_f32_e32 v86, v86
	s_nop 0
	v_add_f32_e32 v197, v86, v197
	s_waitcnt lgkmcnt(1)
	v_mfma_f32_32x32x16_bf16 v[64:79], v[80:83], v[108:111], v[64:79]
	ds_read_b128 v[210:213], v194 offset:128
	v_exp_f32_e32 v83, v87
	v_cvt_pk_bf16_f32 v80, v186, v193
	v_cvt_pk_bf16_f32 v81, v195, v196
	v_cvt_pk_bf16_f32 v82, v84, v85
	v_add_f32_e32 v197, v83, v197
	v_cvt_pk_bf16_f32 v83, v86, v83
	s_waitcnt lgkmcnt(1)
	v_mfma_f32_32x32x16_bf16 v[64:79], v[160:163], v[112:115], v[64:79]
	ds_read_b128 v[84:87], v194 offset:160
	v_exp_f32_e32 v186, v88
	s_nop 0
	v_add_f32_e32 v88, v186, v197
	s_waitcnt lgkmcnt(1)
	v_mfma_f32_32x32x16_bf16 v[64:79], v[210:213], v[116:119], v[64:79]
	ds_read_b128 v[160:163], v194 offset:192
	v_exp_f32_e32 v196, v89
	s_nop 0
	v_add_f32_e32 v88, v196, v88
	s_waitcnt lgkmcnt(1)
; #define LAS __attribute__((address_space(3)))
; template <int DQK, bool MLA> ...
;     ...
; #pragma unroll
;         for (int kk = 0; kk < 2; ++kk) {
;             if (kk == 0) {
; #pragma unroll
;                 for (int d = 0; d < 4; ++d) vf1[d] = *(const LAS bf16x8*)(vb + d * 4608 + 32);
;             } else { const LAS unsigned char* ka = lds + kafter_ofs + r32 * KPITCH + hi * 16; kp0 = *(const LAS bf16x8*)(ka); kp1 = *(const LAS bf16x8*)(ka + 32); }
;             const bf16x8 pb = __builtin_bit_cast(bf16x8, kk ? pw1 : pw0);
; #pragma unroll
;             for (int d = 0; d < 4; ++d) {
;                 o[d] = __builtin_amdgcn_mfma_f32_32x32x16_bf16(kk ? vf1[d] : vf0[d], pb, o[d], 0, 0, 0);
;                 const int e = 4 * kk + d - 2;
;                 if (e >= 0) { const float x = __builtin_amdgcn_exp2f(b[e]); b[e] = x; rs_n += x; }
;             }
;             __builtin_amdgcn_sched_barrier(0);
;         }
;         rs_early = rs_n;
;     };
;     int kc = 0, kn = KT_BYTES, kn2 = 2 * KT_BYTES;
;     for (int t = 0; t < NT; ++t) {
;         const bool has_k2 = (t + 2 < NT), has_v1 = (t + 1 < NT), active = (t <= tmax_w);
;         const int vofs = 3 * KT_BYTES + (t & 1) * VT_BYTES;
;         if (has_k2) gload_k(t + 2);
;         if (has_v1) gload_v(t + 1);
;         if (active) substep(sX, sY, kc + 32 * KPITCH, vofs, 0, kn);
;         if (active) substep(sY, sX, kn, vofs, 1, kn + 32 * KPITCH);
;         if (has_k2) sts_k(kn2);
;         if (has_v1) sts_v((t + 1) & 1);
;         __syncthreads();
;         const int tmp = kc; kc = kn; kn = kn2; kn2 = tmp;
	v_mfma_f32_32x32x16_bf16 v[64:79], v[84:87], v[120:123], v[64:79]
	ds_read_b128 v[210:213], v194 offset:224
	v_exp_f32_e32 v226, v90
	s_nop 0
	v_add_f32_e32 v193, v226, v88
	s_waitcnt lgkmcnt(1)
	v_mfma_f32_32x32x16_bf16 v[64:79], v[160:163], v[124:127], v[64:79]
	ds_read_b128 v[84:87], v194 offset:256
	s_waitcnt lgkmcnt(1)
	v_mfma_f32_32x32x16_bf16 v[64:79], v[210:213], v[128:131], v[64:79]
	ds_read_b128 v[160:163], v194 offset:288
	v_exp_f32_e32 v195, v91
	s_waitcnt lgkmcnt(1)
	v_mfma_f32_32x32x16_bf16 v[64:79], v[84:87], v[136:139], v[64:79]
	ds_read_b128 v[88:91], v194 offset:320
	v_exp_f32_e32 v197, v92
	ds_read_b128 v[84:87], v194 offset:352
	ds_read_b128 v[210:213], v208 offset:64
	ds_read_b128 v[214:217], v208 offset:4672
	ds_read_b128 v[218:221], v208 offset:9280
	ds_read_b128 v[222:225], v208 offset:13888
	s_waitcnt lgkmcnt(6)
	v_mfma_f32_32x32x16_bf16 v[64:79], v[160:163], v[144:147], v[64:79]
	v_exp_f32_e32 v209, v93
	s_waitcnt lgkmcnt(5)
	v_mfma_f32_32x32x16_bf16 v[64:79], v[88:91], v[132:135], v[64:79]
	v_exp_f32_e32 v227, v94
	s_waitcnt lgkmcnt(4)
	v_mfma_f32_32x32x16_bf16 v[64:79], v[84:87], v[140:143], v[64:79]
	v_exp_f32_e32 v229, v95
	v_cvt_pk_bf16_f32 v84, v186, v196
	v_cvt_pk_bf16_f32 v85, v226, v195
	v_cvt_pk_bf16_f32 v86, v197, v209
	v_cvt_pk_bf16_f32 v87, v227, v229
	s_waitcnt lgkmcnt(3)
	v_mfma_f32_32x32x16_bf16 v[48:63], v[210:213], v[80:83], v[48:63]
	s_add_i32 s98, s68, 1
	s_bitcmp1_b32 s98, 0
	s_cselect_b32 s98, 0x4800, 0
	v_add_u32_e32 v230, s71, v172
	v_add_u32_e32 v231, s71, v174
	v_add_u32_e32 v232, s71, v184
	v_add_u32_e32 v233, s98, v173
	s_waitcnt vmcnt(4)
	ds_write_b128 v230, v[148:151]
	v_exp_f32_e32 v64, v64
	v_exp_f32_e32 v65, v65
	s_waitcnt lgkmcnt(3)
	v_mfma_f32_32x32x16_bf16 v[32:47], v[214:217], v[80:83], v[32:47]
	ds_read_b128 v[88:91], v208 offset:96
	ds_read_b128 v[92:95], v208 offset:4704
	ds_read_b128 v[210:213], v208 offset:9312
	ds_read_b128 v[214:217], v208 offset:13920
	s_waitcnt lgkmcnt(6)
	v_mfma_f32_32x32x16_bf16 v[16:31], v[218:221], v[80:83], v[16:31]
	s_waitcnt vmcnt(3)
	ds_write_b128 v231, v[152:155]
	s_waitcnt lgkmcnt(6)
	v_mfma_f32_32x32x16_bf16 v[0:15], v[222:225], v[80:83], v[0:15]
	v_exp_f32_e32 v66, v66
	s_waitcnt vmcnt(2)
	ds_write_b128 v232, v[156:159] offset:256
	s_waitcnt lgkmcnt(5)
	v_mfma_f32_32x32x16_bf16 v[48:63], v[88:91], v[84:87], v[48:63]
	v_exp_f32_e32 v67, v67
	ds_read_b128 v[80:83], v194 offset:12800
	ds_read_b128 v[160:163], v194 offset:12832
	v_exp_f32_e32 v68, v68
	v_mov_b32_e32 v194, v64
	v_exp_f32_e32 v69, v69
	v_pk_add_f32 v[88:89], v[194:195], v[192:193]
	v_mov_b32_e32 v196, v65
	s_waitcnt lgkmcnt(6)
	v_mfma_f32_32x32x16_bf16 v[32:47], v[92:95], v[84:87], v[32:47]
	v_add_f32_e64 v88, v196, v88
	v_add_f32_e64 v89, v197, v89
	v_mov_b32_e32 v208, v66
	v_add_f32_e64 v88, v208, v88
	v_add_f32_e64 v89, v209, v89
	v_mov_b32_e32 v226, v67
	v_pk_add_f32 v[88:89], v[226:227], v[88:89]
	v_mov_b32_e32 v228, v68
	v_pk_add_f32 v[88:89], v[228:229], v[88:89]
	s_waitcnt vmcnt(1)
	ds_write_b128 v233, v[164:167]
	s_waitcnt lgkmcnt(6)
	v_mfma_f32_32x32x16_bf16 v[16:31], v[210:213], v[84:87], v[16:31]
	s_waitcnt vmcnt(0)
	s_add_i32 s68, s68, 1
	s_add_i32 s73, s71, 0
	s_bitcmp1_b32 s68, 0
	s_cselect_b64 s[34:35], -1, 0
	s_and_b64 s[66:67], s[34:35], exec
	s_cselect_b32 s66, 0x4800, 0
	s_and_saveexec_b64 s[66:67], s[4:5]
	ds_write_b128 v233, v[96:99] offset:16384
	s_or_b64 exec, exec, s[66:67]
	ds_write_b128 v233, v[168:171] offset:8192
	v_mov_b32_e32 v186, v69
	v_add_f32_e64 v186, v186, v88
	v_add_f32_e64 v187, v187, v89
	s_cmp_eq_u32 s49, s68
	s_cbranch_scc1 .Lattn_last
	s_mov_b32 s34, s70
	s_mov_b32 s70, s72
	s_mov_b32 s72, s71
	s_mov_b32 s71, s34
	s_bitcmp1_b32 s68, 0
	s_cselect_b32 s34, s87, 0x12c00
	v_add_u32_e32 v193, s70, v183
	v_add_u32_e32 v208, s34, v175
	s_cmp_gt_u32 s68, s48
	s_waitcnt lgkmcnt(7)
	v_mfma_f32_32x32x16_bf16 v[0:15], v[214:217], v[84:87], v[0:15]
	s_branch .Lattn_head
.Lattn_last:
	s_waitcnt lgkmcnt(7)
	v_mfma_f32_32x32x16_bf16 v[0:15], v[214:217], v[84:87], v[0:15]
	s_branch .Lattn_exit
